# G1 epilogue and attention output stores: sc1 nt (write-through plus non-temporal hint) instead of sc1
# baseline (speedup 1.0000x reference)
; #define PG8_STAGE(bufoff, gbase, voff) do { const char* _gb = (const char*)(gbase); asm volatile("" : "+s"(_gb)); _Pragma("unroll") for (int _i = 0; _i < 2; ++_i) \
;         __builtin_amdgcn_global_load_lds((const unsigned*)(_gb + (voff)[_i]), (LAS unsigned*)(lds + (bufoff) + ldsw + _i * 8192), 16, 0, 0); } while (0)
; #define PG8_LDA(dst, b, h) do { _Pragma("unroll") for (int m = 0; m < 4; ++m) _Pragma("unroll") for (int k = 0; k < 2; ++k) dst[m][k] = *(const LAS bf16x8*)(lds + PG8_SA(b, h) + aoff + m * 2048 + k * 1024); } while (0)
; #define PG8_LDB(dst, b, h) do { _Pragma("unroll") for (int n = 0; n < 2; ++n) _Pragma("unroll") for (int k = 0; k < 2; ++k) dst[n][k] = *(const LAS bf16x8*)(lds + PG8_SB(b, h) + boff + n * 2048 + k * 1024); } while (0)
; #define PG8_MMA(ai, bj, At, Bt) do { __builtin_amdgcn_s_setprio(1); _Pragma("unroll") for (int m = 0; m < 4; ++m) _Pragma("unroll") for (int n = 0; n < 2; ++n) _Pragma("unroll") for (int k = 0; k < 2; ++k) \
;         acc[ai][bj][m][n] = __builtin_amdgcn_mfma_f32_16x16x32_bf16(Bt[n][k], At[m][k], acc[ai][bj][m][n], 0, 0, 0); __builtin_amdgcn_s_setprio(0); } while (0)
; #define PG8_WAIT_L(n) asm volatile("s_waitcnt lgkmcnt(" #n ")" ::: "memory")
; #define PG8_BAR __builtin_amdgcn_s_barrier()
; #define PG8_SCHED __builtin_amdgcn_sched_barrier(0)
; template <class Epi, class Sched>
; __device__ __forceinline__ void gemm_phase(LAS unsigned char* lds, const Gemm g, const Sched& S, const Epi& E) {
;     ...
;         for (int t = 0; t < nt; t += 2) {
;             const bool last = (t == nt - 2);
;             const char* a1 = cA + (size_t)(t + 1) * kstep;
;             const char* a2 = last ? nA : cA + (size_t)(t + 2) * kstep; const char* b2 = last ? nB : cB + (size_t)(t + 2) * kstep;
;             const char* a3 = a2 + kstep; const char* b3 = b2 + kstep;
;             PG8_LDB(B0, 0, 0); PG8_SCHED; PG8_LDA(At, 0, 0); PG8_STAGE(PG8_SA(1, 1), a1 + hA, voffA);
;             PG8_WAIT_L(8); PG8_BAR; PG8_WAIT_L(0); PG8_MMA(0, 0, At, B0); PG8_BAR; PG8_SCHED;
;             PG8_LDB(B1, 0, 1); PG8_STAGE(PG8_SB(0, 0), b2, voffB);
;             PG8_BAR; PG8_WAIT_L(0); PG8_MMA(0, 1, At, B1); PG8_BAR;
;             PG8_LDA(At, 0, 1); PG8_STAGE(PG8_SA(0, 0), a2, voffA);
;             PG8_BAR; PG8_WAIT_L(0); PG8_MMA(1, 0, At, B0); PG8_BAR; PG8_SCHED;
.LBB0_74:
	ds_read_b128 v[160:163], v154
	ds_read_b128 v[164:167], v154 offset:1024
	ds_read_b128 v[168:171], v154 offset:2048
	ds_read_b128 v[172:175], v154 offset:3072
	s_add_u32 s12, s10, 0x100
	s_addc_u32 s13, s11, 0
	s_cmp_eq_u32 s43, 12
	s_cselect_b32 s18, s6, s12
	s_cselect_b32 s19, s7, s13
	s_cselect_b32 s14, s40, s41
	s_cselect_b32 s15, s39, s42
	s_add_u32 s16, s18, 0x80
	s_addc_u32 s17, s19, 0
	s_add_u32 s10, s10, 0x40080
	s_addc_u32 s11, s11, 0
	s_mov_b32 m0, s28
	ds_read_b128 v[178:181], v155
	ds_read_b128 v[182:185], v155 offset:1024
	ds_read_b128 v[186:189], v155 offset:2048
	ds_read_b128 v[190:193], v155 offset:3072
	ds_read_b128 v[194:197], v155 offset:4096
	ds_read_b128 v[198:201], v155 offset:5120
	ds_read_b128 v[202:205], v155 offset:6144
	ds_read_b128 v[206:209], v155 offset:7168
	s_nop 0
	v_lshl_add_u64 v[210:211], s[10:11], 0, v[134:135]
	global_load_lds_dwordx4 v[210:211], off
	v_lshl_add_u64 v[210:211], s[10:11], 0, v[130:131]
	s_mov_b32 m0, s29
	s_nop 0
	global_load_lds_dwordx4 v[210:211], off
	s_waitcnt lgkmcnt(8)
	s_barrier
	s_waitcnt lgkmcnt(0)
	s_setprio 1
	s_waitcnt lgkmcnt(0)
	v_mfma_f32_16x16x32_bf16 v[124:127], v[160:163], v[178:181], v[124:127]
	v_mfma_f32_16x16x32_bf16 v[120:123], v[168:171], v[178:181], v[120:123]
	v_mfma_f32_16x16x32_bf16 v[116:119], v[160:163], v[186:189], v[116:119]
	v_mfma_f32_16x16x32_bf16 v[108:111], v[168:171], v[186:189], v[108:111]
	v_mfma_f32_16x16x32_bf16 v[100:103], v[160:163], v[194:197], v[100:103]
	v_mfma_f32_16x16x32_bf16 v[92:95], v[168:171], v[194:197], v[92:95]
	v_mfma_f32_16x16x32_bf16 v[84:87], v[160:163], v[202:205], v[84:87]
	v_mfma_f32_16x16x32_bf16 v[76:79], v[168:171], v[202:205], v[76:79]
	v_mfma_f32_16x16x32_bf16 v[124:127], v[164:167], v[182:185], v[124:127]
	v_mfma_f32_16x16x32_bf16 v[120:123], v[172:175], v[182:185], v[120:123]
	v_mfma_f32_16x16x32_bf16 v[116:119], v[164:167], v[190:193], v[116:119]
	v_mfma_f32_16x16x32_bf16 v[108:111], v[172:175], v[190:193], v[108:111]
	v_mfma_f32_16x16x32_bf16 v[100:103], v[164:167], v[198:201], v[100:103]
	v_mfma_f32_16x16x32_bf16 v[92:95], v[172:175], v[198:201], v[92:95]
	v_mfma_f32_16x16x32_bf16 v[84:87], v[164:167], v[206:209], v[84:87]
	v_mfma_f32_16x16x32_bf16 v[76:79], v[172:175], v[206:209], v[76:79]
	s_setprio 0
	s_barrier
	s_mov_b64 s[10:11], s[14:15]
	s_mov_b32 m0, s30
	ds_read_b128 v[210:213], v156
	ds_read_b128 v[214:217], v156 offset:1024
	ds_read_b128 v[218:221], v156 offset:2048
	ds_read_b128 v[222:225], v156 offset:3072
	s_nop 0
	v_lshl_add_u64 v[226:227], s[10:11], 0, v[132:133]
	global_load_lds_dwordx4 v[226:227], off
	v_lshl_add_u64 v[226:227], s[10:11], 0, v[128:129]
	s_mov_b32 m0, s31
	s_nop 0
	global_load_lds_dwordx4 v[226:227], off
	s_barrier
	s_waitcnt lgkmcnt(0)
	s_setprio 1
	s_waitcnt lgkmcnt(0)
	v_mfma_f32_16x16x32_bf16 v[112:115], v[210:213], v[178:181], v[112:115]
	v_mfma_f32_16x16x32_bf16 v[104:107], v[218:221], v[178:181], v[104:107]
	v_mfma_f32_16x16x32_bf16 v[96:99], v[210:213], v[186:189], v[96:99]
	v_mfma_f32_16x16x32_bf16 v[88:91], v[218:221], v[186:189], v[88:91]
	v_mfma_f32_16x16x32_bf16 v[80:83], v[210:213], v[194:197], v[80:83]
	v_mfma_f32_16x16x32_bf16 v[72:75], v[218:221], v[194:197], v[72:75]
	v_mfma_f32_16x16x32_bf16 v[68:71], v[210:213], v[202:205], v[68:71]
	v_mfma_f32_16x16x32_bf16 v[64:67], v[218:221], v[202:205], v[64:67]
	v_mfma_f32_16x16x32_bf16 v[112:115], v[214:217], v[182:185], v[112:115]
	v_mfma_f32_16x16x32_bf16 v[104:107], v[222:225], v[182:185], v[104:107]
	v_mfma_f32_16x16x32_bf16 v[96:99], v[214:217], v[190:193], v[96:99]
	v_mfma_f32_16x16x32_bf16 v[88:91], v[222:225], v[190:193], v[88:91]
	v_mfma_f32_16x16x32_bf16 v[80:83], v[214:217], v[198:201], v[80:83]
	v_mfma_f32_16x16x32_bf16 v[72:75], v[222:225], v[198:201], v[72:75]
	v_mfma_f32_16x16x32_bf16 v[68:71], v[214:217], v[206:209], v[68:71]
	v_mfma_f32_16x16x32_bf16 v[64:67], v[222:225], v[206:209], v[64:67]
	s_setprio 0
	s_mov_b64 s[10:11], s[18:19]
	s_mov_b32 m0, s3
	s_barrier
	ds_read_b128 v[178:181], v155 offset:16384
	ds_read_b128 v[182:185], v155 offset:17408
	ds_read_b128 v[186:189], v155 offset:18432
	ds_read_b128 v[190:193], v155 offset:19456
	ds_read_b128 v[194:197], v155 offset:20480
	ds_read_b128 v[198:201], v155 offset:21504
	ds_read_b128 v[202:205], v155 offset:22528
	ds_read_b128 v[206:209], v155 offset:23552
	s_nop 0
	v_lshl_add_u64 v[226:227], s[10:11], 0, v[134:135]
	global_load_lds_dwordx4 v[226:227], off
	v_lshl_add_u64 v[226:227], s[10:11], 0, v[130:131]
	s_mov_b32 m0, s22
	s_nop 0
	global_load_lds_dwordx4 v[226:227], off
	s_barrier
	s_waitcnt lgkmcnt(0)
	s_setprio 1
	s_waitcnt lgkmcnt(0)
	v_mfma_f32_16x16x32_bf16 v[60:63], v[160:163], v[178:181], v[60:63]
	v_mfma_f32_16x16x32_bf16 v[56:59], v[168:171], v[178:181], v[56:59]
	v_mfma_f32_16x16x32_bf16 v[52:55], v[160:163], v[186:189], v[52:55]
	v_mfma_f32_16x16x32_bf16 v[44:47], v[168:171], v[186:189], v[44:47]
	v_mfma_f32_16x16x32_bf16 v[36:39], v[160:163], v[194:197], v[36:39]
	v_mfma_f32_16x16x32_bf16 v[28:31], v[168:171], v[194:197], v[28:31]
	v_mfma_f32_16x16x32_bf16 v[20:23], v[160:163], v[202:205], v[20:23]
	v_mfma_f32_16x16x32_bf16 v[12:15], v[168:171], v[202:205], v[12:15]
	v_mfma_f32_16x16x32_bf16 v[60:63], v[164:167], v[182:185], v[60:63]
	v_mfma_f32_16x16x32_bf16 v[56:59], v[172:175], v[182:185], v[56:59]
	v_mfma_f32_16x16x32_bf16 v[52:55], v[164:167], v[190:193], v[52:55]
	v_mfma_f32_16x16x32_bf16 v[44:47], v[172:175], v[190:193], v[44:47]
	v_mfma_f32_16x16x32_bf16 v[36:39], v[164:167], v[198:201], v[36:39]
	v_mfma_f32_16x16x32_bf16 v[28:31], v[172:175], v[198:201], v[28:31]
	v_mfma_f32_16x16x32_bf16 v[20:23], v[164:167], v[206:209], v[20:23]
	v_mfma_f32_16x16x32_bf16 v[12:15], v[172:175], v[206:209], v[12:15]
	s_setprio 0
	s_barrier
; #define PG8_STAGE(bufoff, gbase, voff) do { const char* _gb = (const char*)(gbase); asm volatile("" : "+s"(_gb)); _Pragma("unroll") for (int _i = 0; _i < 2; ++_i) \
;         __builtin_amdgcn_global_load_lds((const unsigned*)(_gb + (voff)[_i]), (LAS unsigned*)(lds + (bufoff) + ldsw + _i * 8192), 16, 0, 0); } while (0)
; #define PG8_LDA(dst, b, h) do { _Pragma("unroll") for (int m = 0; m < 4; ++m) _Pragma("unroll") for (int k = 0; k < 2; ++k) dst[m][k] = *(const LAS bf16x8*)(lds + PG8_SA(b, h) + aoff + m * 2048 + k * 1024); } while (0)
; #define PG8_LDB(dst, b, h) do { _Pragma("unroll") for (int n = 0; n < 2; ++n) _Pragma("unroll") for (int k = 0; k < 2; ++k) dst[n][k] = *(const LAS bf16x8*)(lds + PG8_SB(b, h) + boff + n * 2048 + k * 1024); } while (0)
; #define PG8_MMA(ai, bj, At, Bt) do { __builtin_amdgcn_s_setprio(1); _Pragma("unroll") for (int m = 0; m < 4; ++m) _Pragma("unroll") for (int n = 0; n < 2; ++n) _Pragma("unroll") for (int k = 0; k < 2; ++k) \
;         acc[ai][bj][m][n] = __builtin_amdgcn_mfma_f32_16x16x32_bf16(Bt[n][k], At[m][k], acc[ai][bj][m][n], 0, 0, 0); __builtin_amdgcn_s_setprio(0); } while (0)
; #define PG8_WAIT_V(n) asm volatile("s_waitcnt vmcnt(" #n ")" ::: "memory")
; #define PG8_WAIT_L(n) asm volatile("s_waitcnt lgkmcnt(" #n ")" ::: "memory")
; #define PG8_BAR __builtin_amdgcn_s_barrier()
; #define PG8_SCHED __builtin_amdgcn_sched_barrier(0)
; template <class Epi, class Sched>
; __device__ __forceinline__ void gemm_phase(LAS unsigned char* lds, const Gemm g, const Sched& S, const Epi& E) {
;     ...
;             PG8_STAGE(PG8_SB(0, 1), b2 + hB, voffB);
;             PG8_WAIT_V(6); PG8_BAR; PG8_MMA(1, 1, At, B1); PG8_BAR;
;             PG8_LDB(B0, 1, 0); PG8_SCHED; PG8_LDA(At, 1, 0); PG8_STAGE(PG8_SA(0, 1), a2 + hA, voffA);
;             PG8_WAIT_L(8); PG8_BAR; PG8_WAIT_L(0); PG8_MMA(0, 0, At, B0); PG8_BAR; PG8_SCHED;
;             PG8_LDB(B1, 1, 1); PG8_STAGE(PG8_SB(1, 0), b3, voffB);
;             PG8_BAR; PG8_WAIT_L(0); PG8_MMA(0, 1, At, B1); PG8_BAR;
;             PG8_LDA(At, 1, 1); PG8_STAGE(PG8_SA(1, 0), a3, voffA);
;             PG8_BAR; PG8_WAIT_L(0); PG8_MMA(1, 0, At, B0); PG8_BAR; PG8_SCHED;
	s_add_u32 s10, s14, 0x40000
	s_addc_u32 s11, s15, 0
	s_mov_b32 m0, s33
	s_nop 0
	v_lshl_add_u64 v[160:161], s[10:11], 0, v[132:133]
	global_load_lds_dwordx4 v[160:161], off
	v_lshl_add_u64 v[160:161], s[10:11], 0, v[128:129]
	s_mov_b32 m0, s34
	s_nop 0
	global_load_lds_dwordx4 v[160:161], off
	s_waitcnt vmcnt(6)
	s_barrier
	s_setprio 1
	v_mfma_f32_16x16x32_bf16 v[48:51], v[210:213], v[178:181], v[48:51]
	v_mfma_f32_16x16x32_bf16 v[40:43], v[218:221], v[178:181], v[40:43]
	v_mfma_f32_16x16x32_bf16 v[32:35], v[210:213], v[186:189], v[32:35]
	v_mfma_f32_16x16x32_bf16 v[24:27], v[218:221], v[186:189], v[24:27]
	v_mfma_f32_16x16x32_bf16 v[16:19], v[210:213], v[194:197], v[16:19]
	v_mfma_f32_16x16x32_bf16 v[8:11], v[218:221], v[194:197], v[8:11]
	v_mfma_f32_16x16x32_bf16 v[4:7], v[210:213], v[202:205], v[4:7]
	v_mfma_f32_16x16x32_bf16 v[0:3], v[218:221], v[202:205], v[0:3]
	v_mfma_f32_16x16x32_bf16 v[48:51], v[214:217], v[182:185], v[48:51]
	v_mfma_f32_16x16x32_bf16 v[40:43], v[222:225], v[182:185], v[40:43]
	v_mfma_f32_16x16x32_bf16 v[32:35], v[214:217], v[190:193], v[32:35]
	v_mfma_f32_16x16x32_bf16 v[24:27], v[222:225], v[190:193], v[24:27]
	v_mfma_f32_16x16x32_bf16 v[16:19], v[214:217], v[198:201], v[16:19]
	v_mfma_f32_16x16x32_bf16 v[8:11], v[222:225], v[198:201], v[8:11]
	v_mfma_f32_16x16x32_bf16 v[4:7], v[214:217], v[206:209], v[4:7]
	v_mfma_f32_16x16x32_bf16 v[0:3], v[222:225], v[206:209], v[0:3]
	s_setprio 0
	s_barrier
	ds_read_b128 v[160:163], v158
	ds_read_b128 v[164:167], v158 offset:1024
	ds_read_b128 v[168:171], v158 offset:2048
	ds_read_b128 v[172:175], v158 offset:3072
	s_add_u32 s10, s18, 0x40000
	s_addc_u32 s11, s19, 0
	s_mov_b32 m0, s23
	ds_read_b128 v[178:181], v155 offset:32768
	ds_read_b128 v[182:185], v155 offset:33792
	ds_read_b128 v[186:189], v155 offset:34816
	ds_read_b128 v[190:193], v155 offset:35840
	ds_read_b128 v[194:197], v155 offset:36864
	ds_read_b128 v[198:201], v155 offset:37888
	ds_read_b128 v[202:205], v155 offset:38912
	ds_read_b128 v[206:209], v155 offset:39936
	s_nop 0
	v_lshl_add_u64 v[210:211], s[10:11], 0, v[134:135]
	global_load_lds_dwordx4 v[210:211], off
	v_lshl_add_u64 v[210:211], s[10:11], 0, v[130:131]
	s_mov_b32 m0, s24
	s_nop 0
	global_load_lds_dwordx4 v[210:211], off
	s_waitcnt lgkmcnt(8)
	s_barrier
	s_waitcnt lgkmcnt(0)
	s_setprio 1
	s_waitcnt lgkmcnt(0)
	v_mfma_f32_16x16x32_bf16 v[124:127], v[160:163], v[178:181], v[124:127]
	v_mfma_f32_16x16x32_bf16 v[120:123], v[168:171], v[178:181], v[120:123]
	v_mfma_f32_16x16x32_bf16 v[116:119], v[160:163], v[186:189], v[116:119]
	v_mfma_f32_16x16x32_bf16 v[108:111], v[168:171], v[186:189], v[108:111]
	v_mfma_f32_16x16x32_bf16 v[100:103], v[160:163], v[194:197], v[100:103]
	v_mfma_f32_16x16x32_bf16 v[92:95], v[168:171], v[194:197], v[92:95]
	v_mfma_f32_16x16x32_bf16 v[84:87], v[160:163], v[202:205], v[84:87]
	v_mfma_f32_16x16x32_bf16 v[76:79], v[168:171], v[202:205], v[76:79]
	v_mfma_f32_16x16x32_bf16 v[124:127], v[164:167], v[182:185], v[124:127]
	v_mfma_f32_16x16x32_bf16 v[120:123], v[172:175], v[182:185], v[120:123]
	v_mfma_f32_16x16x32_bf16 v[116:119], v[164:167], v[190:193], v[116:119]
	v_mfma_f32_16x16x32_bf16 v[108:111], v[172:175], v[190:193], v[108:111]
	v_mfma_f32_16x16x32_bf16 v[100:103], v[164:167], v[198:201], v[100:103]
	v_mfma_f32_16x16x32_bf16 v[92:95], v[172:175], v[198:201], v[92:95]
	v_mfma_f32_16x16x32_bf16 v[84:87], v[164:167], v[206:209], v[84:87]
	v_mfma_f32_16x16x32_bf16 v[76:79], v[172:175], v[206:209], v[76:79]
	s_setprio 0
	s_barrier
	s_add_u32 s10, s14, 0x80
	s_addc_u32 s11, s15, 0
	s_add_i32 s18, s35, s21
	ds_read_b128 v[210:213], v159
	ds_read_b128 v[214:217], v159 offset:1024
	ds_read_b128 v[218:221], v159 offset:2048
	ds_read_b128 v[222:225], v159 offset:3072
	s_mov_b32 m0, s18
	v_lshl_add_u64 v[226:227], s[10:11], 0, v[132:133]
	global_load_lds_dwordx4 v[226:227], off
	v_lshl_add_u64 v[226:227], s[10:11], 0, v[128:129]
	s_add_i32 m0, s18, 0x2000
	s_nop 0
	global_load_lds_dwordx4 v[226:227], off
	s_barrier
	s_waitcnt lgkmcnt(0)
	s_setprio 1
	s_waitcnt lgkmcnt(0)
	v_mfma_f32_16x16x32_bf16 v[112:115], v[210:213], v[178:181], v[112:115]
	v_mfma_f32_16x16x32_bf16 v[104:107], v[218:221], v[178:181], v[104:107]
	v_mfma_f32_16x16x32_bf16 v[96:99], v[210:213], v[186:189], v[96:99]
	v_mfma_f32_16x16x32_bf16 v[88:91], v[218:221], v[186:189], v[88:91]
	v_mfma_f32_16x16x32_bf16 v[80:83], v[210:213], v[194:197], v[80:83]
	v_mfma_f32_16x16x32_bf16 v[72:75], v[218:221], v[194:197], v[72:75]
	v_mfma_f32_16x16x32_bf16 v[68:71], v[210:213], v[202:205], v[68:71]
	v_mfma_f32_16x16x32_bf16 v[64:67], v[218:221], v[202:205], v[64:67]
	v_mfma_f32_16x16x32_bf16 v[112:115], v[214:217], v[182:185], v[112:115]
	v_mfma_f32_16x16x32_bf16 v[104:107], v[222:225], v[182:185], v[104:107]
	v_mfma_f32_16x16x32_bf16 v[96:99], v[214:217], v[190:193], v[96:99]
	v_mfma_f32_16x16x32_bf16 v[88:91], v[222:225], v[190:193], v[88:91]
	v_mfma_f32_16x16x32_bf16 v[80:83], v[214:217], v[198:201], v[80:83]
	v_mfma_f32_16x16x32_bf16 v[72:75], v[222:225], v[198:201], v[72:75]
	v_mfma_f32_16x16x32_bf16 v[68:71], v[214:217], v[206:209], v[68:71]
	v_mfma_f32_16x16x32_bf16 v[64:67], v[222:225], v[206:209], v[64:67]
	s_setprio 0
	s_mov_b32 m0, s25
	s_barrier
	ds_read_b128 v[178:181], v155 offset:49152
	ds_read_b128 v[182:185], v155 offset:50176
	ds_read_b128 v[186:189], v155 offset:51200
	ds_read_b128 v[190:193], v155 offset:52224
	ds_read_b128 v[194:197], v155 offset:53248
	ds_read_b128 v[198:201], v155 offset:54272
	ds_read_b128 v[202:205], v155 offset:55296
	ds_read_b128 v[206:209], v155 offset:56320
	s_nop 0
	v_lshl_add_u64 v[226:227], s[16:17], 0, v[134:135]
	global_load_lds_dwordx4 v[226:227], off
	v_lshl_add_u64 v[226:227], s[16:17], 0, v[130:131]
	s_mov_b32 m0, s26
	s_nop 0
	global_load_lds_dwordx4 v[226:227], off
	s_barrier
; __device__ __forceinline__ unsigned cvt_pk(float lo, float hi) { unsigned r; asm volatile("v_cvt_pk_bf16_f32 %0, %1, %2" : "=v"(r) : "v"(lo), "v"(hi)); return r; }
; #define PG8_STAGE(bufoff, gbase, voff) do { const char* _gb = (const char*)(gbase); asm volatile("" : "+s"(_gb)); _Pragma("unroll") for (int _i = 0; _i < 2; ++_i) \
;         __builtin_amdgcn_global_load_lds((const unsigned*)(_gb + (voff)[_i]), (LAS unsigned*)(lds + (bufoff) + ldsw + _i * 8192), 16, 0, 0); } while (0)
; #define PG8_MMA(ai, bj, At, Bt) do { __builtin_amdgcn_s_setprio(1); _Pragma("unroll") for (int m = 0; m < 4; ++m) _Pragma("unroll") for (int n = 0; n < 2; ++n) _Pragma("unroll") for (int k = 0; k < 2; ++k) \
;         acc[ai][bj][m][n] = __builtin_amdgcn_mfma_f32_16x16x32_bf16(Bt[n][k], At[m][k], acc[ai][bj][m][n], 0, 0, 0); __builtin_amdgcn_s_setprio(0); } while (0)
; #define PG8_WAIT_V(n) asm volatile("s_waitcnt vmcnt(" #n ")" ::: "memory")
; #define PG8_WAIT_L(n) asm volatile("s_waitcnt lgkmcnt(" #n ")" ::: "memory")
; #define PG8_BAR __builtin_amdgcn_s_barrier()
; #define PG8_SCHED __builtin_amdgcn_sched_barrier(0)
; template <class Epi, class Sched>
; __device__ __forceinline__ void gemm_phase(LAS unsigned char* lds, const Gemm g, const Sched& S, const Epi& E) {
;     ...
;             PG8_BAR; PG8_WAIT_L(0); PG8_MMA(1, 0, At, B0); PG8_BAR; PG8_SCHED;
;             PG8_STAGE(PG8_SB(1, 1), b3 + hB, voffB);
;             PG8_WAIT_V(6); PG8_BAR; PG8_MMA(1, 1, At, B1); PG8_BAR;
;         }
;     __device__ __forceinline__ void operator()(const f32x4 (&acc)[2][2][4][2], const Unit& u, int wr, int wc, int fr, int fq) const {
;         const int row0 = u.pm * BM + wr * 64 + fr;
;         if (u.pn < 12) {
;             const int col0 = u.pn * BM + wc * 32 + 8 * fq;
; #pragma unroll
;             for (int ai = 0; ai < 2; ++ai)
; #pragma unroll
;                 for (int m = 0; m < 4; ++m) { bf16_t* rowp = P0 + (size_t)(row0 + ai * HALF + m * 16) * LDP + col0;
; #pragma unroll
;                     for (int bj = 0; bj < 2; ++bj) { const f32x4 v0 = acc[ai][bj][m][0], v1 = acc[ai][bj][m][1];
;                         u32x4 w; w.x = cvt_pk(v0[0], v0[1]); w.y = cvt_pk(v0[2], v0[3]); w.z = cvt_pk(v1[0], v1[1]); w.w = cvt_pk(v1[2], v1[3]);
;                         *(u32x4*)(rowp + bj * HALF) = w; } }
	s_waitcnt lgkmcnt(0)
	s_setprio 1
	s_waitcnt lgkmcnt(0)
	v_mfma_f32_16x16x32_bf16 v[60:63], v[160:163], v[178:181], v[60:63]
	v_mfma_f32_16x16x32_bf16 v[56:59], v[168:171], v[178:181], v[56:59]
	v_mfma_f32_16x16x32_bf16 v[52:55], v[160:163], v[186:189], v[52:55]
	v_mfma_f32_16x16x32_bf16 v[44:47], v[168:171], v[186:189], v[44:47]
	v_mfma_f32_16x16x32_bf16 v[36:39], v[160:163], v[194:197], v[36:39]
	v_mfma_f32_16x16x32_bf16 v[28:31], v[168:171], v[194:197], v[28:31]
	v_mfma_f32_16x16x32_bf16 v[20:23], v[160:163], v[202:205], v[20:23]
	v_mfma_f32_16x16x32_bf16 v[12:15], v[168:171], v[202:205], v[12:15]
	v_mfma_f32_16x16x32_bf16 v[60:63], v[164:167], v[182:185], v[60:63]
	v_mfma_f32_16x16x32_bf16 v[56:59], v[172:175], v[182:185], v[56:59]
	v_mfma_f32_16x16x32_bf16 v[52:55], v[164:167], v[190:193], v[52:55]
	v_mfma_f32_16x16x32_bf16 v[44:47], v[172:175], v[190:193], v[44:47]
	v_mfma_f32_16x16x32_bf16 v[36:39], v[164:167], v[198:201], v[36:39]
	v_mfma_f32_16x16x32_bf16 v[28:31], v[172:175], v[198:201], v[28:31]
	v_mfma_f32_16x16x32_bf16 v[20:23], v[164:167], v[206:209], v[20:23]
	v_mfma_f32_16x16x32_bf16 v[12:15], v[172:175], v[206:209], v[12:15]
	s_setprio 0
	s_barrier
	s_add_u32 s10, s14, 0x40080
	s_addc_u32 s11, s15, 0
	s_add_i32 s14, s36, s21
	s_mov_b32 m0, s14
	v_lshl_add_u64 v[160:161], s[10:11], 0, v[132:133]
	global_load_lds_dwordx4 v[160:161], off
	v_lshl_add_u64 v[160:161], s[10:11], 0, v[128:129]
	s_add_i32 m0, s14, 0x2000
	s_nop 0
	global_load_lds_dwordx4 v[160:161], off
	s_waitcnt vmcnt(6)
	s_barrier
	s_setprio 1
	v_mfma_f32_16x16x32_bf16 v[48:51], v[210:213], v[178:181], v[48:51]
	v_mfma_f32_16x16x32_bf16 v[40:43], v[218:221], v[178:181], v[40:43]
	v_mfma_f32_16x16x32_bf16 v[32:35], v[210:213], v[186:189], v[32:35]
	v_mfma_f32_16x16x32_bf16 v[24:27], v[218:221], v[186:189], v[24:27]
	v_mfma_f32_16x16x32_bf16 v[16:19], v[210:213], v[194:197], v[16:19]
	v_mfma_f32_16x16x32_bf16 v[8:11], v[218:221], v[194:197], v[8:11]
	v_mfma_f32_16x16x32_bf16 v[4:7], v[210:213], v[202:205], v[4:7]
	v_mfma_f32_16x16x32_bf16 v[0:3], v[218:221], v[202:205], v[0:3]
	v_mfma_f32_16x16x32_bf16 v[48:51], v[214:217], v[182:185], v[48:51]
	v_mfma_f32_16x16x32_bf16 v[40:43], v[222:225], v[182:185], v[40:43]
	v_mfma_f32_16x16x32_bf16 v[32:35], v[214:217], v[190:193], v[32:35]
	v_mfma_f32_16x16x32_bf16 v[24:27], v[222:225], v[190:193], v[24:27]
	v_mfma_f32_16x16x32_bf16 v[16:19], v[214:217], v[198:201], v[16:19]
	v_mfma_f32_16x16x32_bf16 v[8:11], v[222:225], v[198:201], v[8:11]
	v_mfma_f32_16x16x32_bf16 v[4:7], v[214:217], v[206:209], v[4:7]
	v_mfma_f32_16x16x32_bf16 v[0:3], v[222:225], v[206:209], v[0:3]
	s_setprio 0
	s_add_i32 s43, s43, 2
	s_add_u32 s41, s41, 0x100
	s_addc_u32 s42, s42, 0
	s_cmp_gt_u32 s43, 13
	s_mov_b64 s[10:11], s[12:13]
	s_barrier
	s_cbranch_scc0 .LBB0_74
	v_lshl_or_b32 v136, s38, 9, v157
	v_lshl_add_u64 v[160:161], v[138:139], 0, v[136:137]
	v_cvt_pk_bf16_f32 v124, v124, v125
	v_cvt_pk_bf16_f32 v125, v126, v127
	v_cvt_pk_bf16_f32 v126, v120, v121
	v_cvt_pk_bf16_f32 v127, v122, v123
	global_store_dwordx4 v[160:161], v[124:127], off sc1 nt
	v_cvt_pk_bf16_f32 v112, v112, v113
	v_cvt_pk_bf16_f32 v113, v114, v115
	v_cvt_pk_bf16_f32 v114, v104, v105
	v_cvt_pk_bf16_f32 v115, v106, v107
	global_store_dwordx4 v[160:161], v[112:115], off offset:256 sc1 nt
	v_cvt_pk_bf16_f32 v104, v116, v117
	v_cvt_pk_bf16_f32 v105, v118, v119
	v_cvt_pk_bf16_f32 v106, v108, v109
	v_cvt_pk_bf16_f32 v107, v110, v111
	s_cmp_eq_u32 s37, 12
	s_nop 0
	v_lshl_add_u64 v[112:113], v[140:141], 0, v[136:137]
	global_store_dwordx4 v[112:113], v[104:107], off sc1 nt
	v_cvt_pk_bf16_f32 v96, v96, v97
	v_cvt_pk_bf16_f32 v97, v98, v99
	v_cvt_pk_bf16_f32 v98, v88, v89
	v_cvt_pk_bf16_f32 v99, v90, v91
	global_store_dwordx4 v[112:113], v[96:99], off offset:256 sc1 nt
	v_cvt_pk_bf16_f32 v88, v100, v101
	v_cvt_pk_bf16_f32 v89, v102, v103
	v_cvt_pk_bf16_f32 v90, v92, v93
	v_cvt_pk_bf16_f32 v91, v94, v95
	s_mov_b32 s38, s37
	s_nop 0
	v_lshl_add_u64 v[96:97], v[142:143], 0, v[136:137]
	global_store_dwordx4 v[96:97], v[88:91], off sc1 nt
	v_cvt_pk_bf16_f32 v80, v80, v81
	v_cvt_pk_bf16_f32 v81, v82, v83
	v_cvt_pk_bf16_f32 v82, v72, v73
	v_cvt_pk_bf16_f32 v83, v74, v75
	global_store_dwordx4 v[96:97], v[80:83], off offset:256 sc1 nt
	v_cvt_pk_bf16_f32 v72, v84, v85
	v_cvt_pk_bf16_f32 v73, v86, v87
	v_cvt_pk_bf16_f32 v74, v76, v77
	v_cvt_pk_bf16_f32 v75, v78, v79
	s_mov_b64 s[10:11], s[8:9]
	s_nop 0
	v_lshl_add_u64 v[80:81], v[144:145], 0, v[136:137]
	global_store_dwordx4 v[80:81], v[72:75], off sc1 nt
	v_cvt_pk_bf16_f32 v68, v68, v69
	v_cvt_pk_bf16_f32 v69, v70, v71
	v_cvt_pk_bf16_f32 v70, v64, v65
	v_lshl_add_u64 v[64:65], v[146:147], 0, v[136:137]
	v_cvt_pk_bf16_f32 v71, v66, v67
	global_store_dwordx4 v[80:81], v[68:71], off offset:256 sc1 nt
	v_cvt_pk_bf16_f32 v60, v60, v61
	v_cvt_pk_bf16_f32 v61, v62, v63
	v_cvt_pk_bf16_f32 v62, v56, v57
	v_cvt_pk_bf16_f32 v63, v58, v59
	global_store_dwordx4 v[64:65], v[60:63], off sc1 nt
	v_cvt_pk_bf16_f32 v48, v48, v49
	v_cvt_pk_bf16_f32 v49, v50, v51
	v_cvt_pk_bf16_f32 v50, v40, v41
	v_cvt_pk_bf16_f32 v51, v42, v43
	global_store_dwordx4 v[64:65], v[48:51], off offset:256 sc1 nt
	v_cvt_pk_bf16_f32 v40, v52, v53
	v_cvt_pk_bf16_f32 v41, v54, v55
	v_cvt_pk_bf16_f32 v42, v44, v45
	v_cvt_pk_bf16_f32 v43, v46, v47
	s_nop 1
	v_lshl_add_u64 v[48:49], v[148:149], 0, v[136:137]
	global_store_dwordx4 v[48:49], v[40:43], off sc1 nt
	v_cvt_pk_bf16_f32 v32, v32, v33
	v_cvt_pk_bf16_f32 v33, v34, v35
	v_cvt_pk_bf16_f32 v34, v24, v25
	v_cvt_pk_bf16_f32 v35, v26, v27
	global_store_dwordx4 v[48:49], v[32:35], off offset:256 sc1 nt
	v_cvt_pk_bf16_f32 v24, v36, v37
	v_cvt_pk_bf16_f32 v25, v38, v39
	v_cvt_pk_bf16_f32 v26, v28, v29
	v_cvt_pk_bf16_f32 v27, v30, v31
	s_nop 1
	v_lshl_add_u64 v[32:33], v[150:151], 0, v[136:137]
	global_store_dwordx4 v[32:33], v[24:27], off sc1 nt
	v_cvt_pk_bf16_f32 v16, v16, v17
	v_cvt_pk_bf16_f32 v17, v18, v19
	v_cvt_pk_bf16_f32 v18, v8, v9
	v_cvt_pk_bf16_f32 v19, v10, v11
	global_store_dwordx4 v[32:33], v[16:19], off offset:256 sc1 nt
	v_cvt_pk_bf16_f32 v8, v20, v21
	v_cvt_pk_bf16_f32 v9, v22, v23
	v_cvt_pk_bf16_f32 v10, v12, v13
	v_cvt_pk_bf16_f32 v11, v14, v15
	s_nop 1
	v_lshl_add_u64 v[16:17], v[152:153], 0, v[136:137]
	global_store_dwordx4 v[16:17], v[8:11], off sc1 nt
	v_cvt_pk_bf16_f32 v4, v4, v5
	v_cvt_pk_bf16_f32 v5, v6, v7
	v_cvt_pk_bf16_f32 v6, v0, v1
	v_cvt_pk_bf16_f32 v7, v2, v3
	global_store_dwordx4 v[16:17], v[4:7], off offset:256 sc1 nt
	s_cbranch_scc0 .LBB0_73
	s_waitcnt vmcnt(0)
	s_cmpk_gt_u32 s20, 0xff
	s_cbranch_scc1 .LBB0_78
	s_barrier

; __device__ __forceinline__ int crow(int r, int hi) { return (r & 3) + 8 * (r >> 2) + 4 * hi; }
; __device__ __forceinline__ void attn_body(const bf16_t* __restrict__ Qb, const bf16_t* __restrict__ Kh, const bf16_t* __restrict__ Vh, const bf16_t* __restrict__ Zb, ...
;     ...
;     if (hi == 0) li_l[r32] = l_reg; asm volatile("s_waitcnt lgkmcnt(0)" ::: "memory");
;     float rli[16];
; #pragma unroll
;     for (int r = 0; r < 16; ++r) rli[r] = __builtin_amdgcn_rcpf(li_l[crow(r, hi)]);
;     u32x4 zr[8];
; #pragma unroll
;     for (int i = 0; i < 8; ++i) { const int idx = tid + 512 * i; zr[i] = *(const u32x4*)(Zb + (long)(idx >> 4) * LDP + (idx & 15) * 8); }
;     __syncthreads();
;     float* Ol = (float*)lds;
; #pragma unroll
;     for (int r = 0; r < 16; ++r) { const int orow = wid * QBLK + crow(r, hi);
; #pragma unroll
;         for (int d0 = 0; d0 < 4; ++d0) Ol[orow * 132 + d0 * 32 + r32] = o[d0][r] * rli[r]; }
;     __syncthreads();
.LBB0_480:
	s_or_b64 exec, exec, s[6:7]
	s_waitcnt lgkmcnt(0)
	v_add_u32_e32 v72, v66, v184
	ds_read_b128 v[64:67], v72
	ds_read_b128 v[68:71], v72 offset:32
	v_mov_b32_e32 v189, v185
	v_lshl_or_b32 v125, v199, 2, v202
	v_lshlrev_b32_e32 v126, 2, v201
	s_waitcnt lgkmcnt(1)
	v_rcp_f32_e32 v85, v64
	v_rcp_f32_e32 v110, v65
	v_rcp_f32_e32 v111, v66
	v_rcp_f32_e32 v112, v67
	s_waitcnt lgkmcnt(0)
	v_rcp_f32_e32 v113, v68
	ds_read_b128 v[64:67], v72 offset:64
	v_rcp_f32_e32 v114, v69
	v_rcp_f32_e32 v115, v70
	v_rcp_f32_e32 v116, v71
	ds_read_b128 v[68:71], v72 offset:96
	s_waitcnt lgkmcnt(1)
	v_rcp_f32_e32 v117, v64
	v_rcp_f32_e32 v118, v65
	v_lshl_add_u64 v[64:65], s[16:17], 0, v[188:189]
	v_rcp_f32_e32 v119, v66
	s_waitcnt lgkmcnt(0)
	v_rcp_f32_e32 v121, v68
	v_add_u32_e32 v68, 0x200, v200
	v_rcp_f32_e32 v120, v67
	v_mad_i64_i32 v[66:67], s[16:17], v186, s30, v[64:65]
	v_ashrrev_i32_e32 v108, 4, v68
	v_rcp_f32_e32 v122, v69
	v_mad_i64_i32 v[68:69], s[16:17], v108, s30, v[64:65]
	global_load_dwordx4 v[96:99], v[66:67], off offset:3072
	global_load_dwordx4 v[100:103], v[68:69], off offset:3072
	v_add_u32_e32 v66, 0x400, v200
	v_ashrrev_i32_e32 v94, 4, v66
	v_add_u32_e32 v68, 0x600, v200
	v_mad_i64_i32 v[66:67], s[16:17], v94, s30, v[64:65]
	v_ashrrev_i32_e32 v92, 4, v68
	v_mad_i64_i32 v[68:69], s[16:17], v92, s30, v[64:65]
	global_load_dwordx4 v[104:107], v[66:67], off offset:3072
	global_load_dwordx4 v[80:83], v[68:69], off offset:3072
	v_add_u32_e32 v66, 0x800, v200
	v_add_u32_e32 v68, 0xa00, v200
	v_ashrrev_i32_e32 v90, 4, v66
	v_ashrrev_i32_e32 v88, 4, v68
	v_mad_i64_i32 v[66:67], s[16:17], v90, s30, v[64:65]
	v_mad_i64_i32 v[68:69], s[16:17], v88, s30, v[64:65]
	global_load_dwordx4 v[76:79], v[66:67], off offset:3072
	global_load_dwordx4 v[72:75], v[68:69], off offset:3072
	v_add_u32_e32 v66, 0xc00, v200
	v_add_u32_e32 v68, 0xe00, v200
	v_ashrrev_i32_e32 v86, 4, v66
	v_ashrrev_i32_e32 v84, 4, v68
	v_mul_lo_u32 v125, v125, s37
	v_mad_i64_i32 v[66:67], s[16:17], v86, s30, v[64:65]
	v_mad_i64_i32 v[64:65], s[16:17], v84, s30, v[64:65]
	v_add3_u32 v125, 0, v126, v125
	v_mul_f32_e32 v0, v0, v85
	v_mul_f32_e32 v16, v16, v85
	v_rcp_f32_e32 v123, v70
	v_rcp_f32_e32 v124, v71
	global_load_dwordx4 v[68:71], v[66:67], off offset:3072
	s_nop 0
	global_load_dwordx4 v[64:67], v[64:65], off offset:3072
	s_barrier
	ds_write2_b32 v125, v0, v16 offset1:32
	v_mul_f32_e32 v0, v32, v85
	v_mul_f32_e32 v16, v48, v85
	ds_write2_b32 v125, v0, v16 offset0:64 offset1:96
	v_mul_f32_e32 v0, v1, v110
	v_mul_f32_e32 v1, v17, v110
	ds_write2_b32 v125, v0, v1 offset0:132 offset1:164
	v_mul_f32_e32 v0, v33, v110
	v_mul_f32_e32 v1, v49, v110
	ds_write2_b32 v125, v0, v1 offset0:196 offset1:228
	v_mul_f32_e32 v0, v2, v111
	v_mul_f32_e32 v1, v18, v111
	v_add_u32_e32 v2, 0x400, v125
	ds_write2_b32 v2, v0, v1 offset0:8 offset1:40
	v_mul_f32_e32 v0, v34, v111
	v_mul_f32_e32 v1, v50, v111
	ds_write2_b32 v2, v0, v1 offset0:72 offset1:104
	v_mul_f32_e32 v0, v3, v112
	v_mul_f32_e32 v1, v19, v112
	ds_write2_b32 v2, v0, v1 offset0:140 offset1:172
	v_mul_f32_e32 v0, v35, v112
	v_mul_f32_e32 v1, v51, v112
	ds_write2_b32 v2, v0, v1 offset0:204 offset1:236
	v_mul_f32_e32 v0, v4, v113
	v_mul_f32_e32 v1, v20, v113
	v_add_u32_e32 v2, 0x1000, v125
	ds_write2_b32 v2, v0, v1 offset0:32 offset1:64
	v_mul_f32_e32 v0, v36, v113
	v_mul_f32_e32 v1, v52, v113
	ds_write2_b32 v2, v0, v1 offset0:96 offset1:128
	v_mul_f32_e32 v0, v5, v114
	v_mul_f32_e32 v1, v21, v114
	ds_write2_b32 v2, v0, v1 offset0:164 offset1:196
	v_mul_f32_e32 v0, v37, v114
	v_mul_f32_e32 v1, v53, v114
	v_add_u32_e32 v2, 0x1200, v125
	ds_write2_b32 v2, v0, v1 offset0:100 offset1:132
	v_mul_f32_e32 v0, v6, v115
	v_mul_f32_e32 v1, v22, v115
	v_add_u32_e32 v2, 0x1400, v125
	ds_write2_b32 v2, v0, v1 offset0:40 offset1:72
	v_mul_f32_e32 v0, v38, v115
	v_mul_f32_e32 v1, v54, v115
	ds_write2_b32 v2, v0, v1 offset0:104 offset1:136
	v_mul_f32_e32 v0, v7, v116
	v_mul_f32_e32 v1, v23, v116
	ds_write2_b32 v2, v0, v1 offset0:172 offset1:204
	v_mul_f32_e32 v0, v39, v116
	v_mul_f32_e32 v1, v55, v116
	v_add_u32_e32 v2, 0x1600, v125
	ds_write2_b32 v2, v0, v1 offset0:108 offset1:140
	v_mul_f32_e32 v0, v8, v117
	v_mul_f32_e32 v1, v24, v117
	v_add_u32_e32 v2, 0x2000, v125
	ds_write2_b32 v2, v0, v1 offset0:64 offset1:96
	v_mul_f32_e32 v0, v40, v117
	v_mul_f32_e32 v1, v56, v117
	ds_write2_b32 v2, v0, v1 offset0:128 offset1:160
	v_mul_f32_e32 v0, v9, v118
	v_mul_f32_e32 v1, v25, v118
	ds_write2_b32 v2, v0, v1 offset0:196 offset1:228
	v_mul_f32_e32 v0, v41, v118
	v_mul_f32_e32 v1, v57, v118
	v_add_u32_e32 v2, 0x2400, v125
	ds_write2_b32 v2, v0, v1 offset0:4 offset1:36
	v_mul_f32_e32 v0, v10, v119
	v_mul_f32_e32 v1, v26, v119
	ds_write2_b32 v2, v0, v1 offset0:72 offset1:104
	v_mul_f32_e32 v0, v42, v119
	v_mul_f32_e32 v1, v58, v119
	ds_write2_b32 v2, v0, v1 offset0:136 offset1:168
	v_mul_f32_e32 v0, v11, v120
	v_mul_f32_e32 v1, v27, v120
	ds_write2_b32 v2, v0, v1 offset0:204 offset1:236
	v_mul_f32_e32 v0, v43, v120
	v_mul_f32_e32 v1, v59, v120
	v_add_u32_e32 v2, 0x2800, v125
	ds_write2_b32 v2, v0, v1 offset0:12 offset1:44
	v_mul_f32_e32 v0, v12, v121
	v_mul_f32_e32 v1, v28, v121
	v_add_u32_e32 v2, 0x3000, v125
	ds_write2_b32 v2, v0, v1 offset0:96 offset1:128
	v_mul_f32_e32 v0, v44, v121
	v_mul_f32_e32 v1, v60, v121
	ds_write2_b32 v2, v0, v1 offset0:160 offset1:192
	v_mul_f32_e32 v0, v13, v122
	v_mul_f32_e32 v1, v29, v122
	v_add_u32_e32 v2, 0x3200, v125
	ds_write2_b32 v2, v0, v1 offset0:100 offset1:132
	v_mul_f32_e32 v0, v45, v122
	v_mul_f32_e32 v1, v61, v122
	v_add_u32_e32 v2, 0x3400, v125
	ds_write2_b32 v2, v0, v1 offset0:36 offset1:68
	v_mul_f32_e32 v0, v14, v123
	v_mul_f32_e32 v1, v30, v123
	ds_write2_b32 v2, v0, v1 offset0:104 offset1:136
	v_mul_f32_e32 v0, v46, v123
	v_mul_f32_e32 v1, v62, v123
	ds_write2_b32 v2, v0, v1 offset0:168 offset1:200
	v_mul_f32_e32 v0, v15, v124
	v_mul_f32_e32 v1, v31, v124
	v_add_u32_e32 v2, 0x3600, v125
	v_lshl_add_u32 v8, v198, 2, 0
	ds_write2_b32 v2, v0, v1 offset0:108 offset1:140
	v_mul_f32_e32 v0, v47, v124
	v_mul_f32_e32 v1, v63, v124
	v_add_u32_e32 v2, 0x3800, v125
	v_mad_u64_u32 v[4:5], s[16:17], v186, s37, v[8:9]
	ds_write2_b32 v2, v0, v1 offset0:44 offset1:76
	s_waitcnt lgkmcnt(0)
	s_barrier
; __device__ __forceinline__ unsigned cvt_pk(float lo, float hi) { unsigned r; asm volatile("v_cvt_pk_bf16_f32 %0, %1, %2" : "=v"(r) : "v"(lo), "v"(hi)); return r; }
; __device__ __forceinline__ float bflo(unsigned w) { return __uint_as_float(w << 16); }
; __device__ __forceinline__ float bfhi(unsigned w) { return __uint_as_float(w & 0xffff0000u); }
; __device__ __forceinline__ void attn_body(const bf16_t* __restrict__ Qb, const bf16_t* __restrict__ Kh, const bf16_t* __restrict__ Vh, const bf16_t* __restrict__ Zb, ...
;     ...
; #pragma unroll
;     for (int i = 0; i < 8; ++i) { const int idx = tid + 512 * i, row = idx >> 4, c8 = (idx & 15) * 8;
;         const f32x4 a = *(const f32x4*)(Ol + row * 132 + c8), b = *(const f32x4*)(Ol + row * 132 + c8 + 4);
;         const u32x4 z = zr[i];
;         u32x4 w; w.x = cvt_pk(a[0] * bflo(z.x), a[1] * bfhi(z.x)); w.y = cvt_pk(a[2] * bflo(z.y), a[3] * bfhi(z.y));
;         w.z = cvt_pk(b[0] * bflo(z.z), b[1] * bfhi(z.z)); w.w = cvt_pk(b[2] * bflo(z.w), b[3] * bfhi(z.w));
;         *(u32x4*)(Ob + (long)row * 1024 + c8) = w; }
	ds_read_b128 v[0:3], v4
	s_waitcnt vmcnt(7)
	v_lshlrev_b32_e32 v9, 16, v96
	ds_read_b128 v[4:7], v4 offset:16
	s_lshl_b64 s[6:7], s[8:9], 11
	v_readlane_b32 s20, v254, 46
	s_waitcnt lgkmcnt(1)
	v_mul_f32_e32 v0, v0, v9
	v_and_b32_e32 v9, 0xffff0000, v96
	v_mul_f32_e32 v1, v1, v9
	v_cvt_pk_bf16_f32 v0, v0, v1
	v_lshlrev_b32_e32 v1, 16, v97
	v_mul_f32_e32 v1, v2, v1
	v_and_b32_e32 v2, 0xffff0000, v97
	v_readlane_b32 s21, v254, 47
	s_add_u32 s6, s20, s6
	v_mul_f32_e32 v2, v3, v2
	s_addc_u32 s7, s21, s7
	v_cvt_pk_bf16_f32 v1, v1, v2
	v_lshlrev_b32_e32 v2, 16, v98
	v_and_b32_e32 v3, 0xffff0000, v98
	s_add_u32 s6, s6, s18
	s_waitcnt lgkmcnt(0)
	v_mul_f32_e32 v2, v4, v2
	v_mul_f32_e32 v3, v5, v3
	s_addc_u32 s7, s7, s19
	v_cvt_pk_bf16_f32 v2, v2, v3
	v_lshlrev_b32_e32 v3, 16, v99
	v_and_b32_e32 v4, 0xffff0000, v99
	v_lshl_add_u64 v[10:11], s[6:7], 0, v[188:189]
	v_mul_f32_e32 v3, v6, v3
	v_mul_f32_e32 v4, v7, v4
	v_mad_u64_u32 v[14:15], s[6:7], v108, s37, v[8:9]
	v_cvt_pk_bf16_f32 v3, v3, v4
	ds_read_b128 v[4:7], v14
	v_lshlrev_b64 v[12:13], 11, v[186:187]
	v_lshl_add_u64 v[12:13], v[10:11], 0, v[12:13]
	s_waitcnt vmcnt(6)
	v_lshlrev_b32_e32 v9, 16, v100
	global_store_dwordx4 v[12:13], v[0:3], off sc1 nt
	ds_read_b128 v[0:3], v14 offset:16
	s_waitcnt lgkmcnt(1)
	v_mul_f32_e32 v4, v4, v9
	v_and_b32_e32 v9, 0xffff0000, v100
	v_mul_f32_e32 v5, v5, v9
	v_cvt_pk_bf16_f32 v4, v4, v5
	v_lshlrev_b32_e32 v5, 16, v101
	v_mul_f32_e32 v5, v6, v5
	v_and_b32_e32 v6, 0xffff0000, v101
	v_mul_f32_e32 v6, v7, v6
	v_cvt_pk_bf16_f32 v5, v5, v6
	v_lshlrev_b32_e32 v6, 16, v102
	s_waitcnt lgkmcnt(0)
	v_mul_f32_e32 v0, v0, v6
	v_and_b32_e32 v6, 0xffff0000, v102
	v_mul_f32_e32 v1, v1, v6
	v_cvt_pk_bf16_f32 v6, v0, v1
	v_lshlrev_b32_e32 v0, 16, v103
	v_and_b32_e32 v1, 0xffff0000, v103
	v_mul_f32_e32 v0, v2, v0
	v_mul_f32_e32 v1, v3, v1
	v_mad_u64_u32 v[14:15], s[6:7], v94, s37, v[8:9]
	v_cvt_pk_bf16_f32 v7, v0, v1
	ds_read_b128 v[0:3], v14
	v_ashrrev_i32_e32 v109, 31, v108
	v_lshlrev_b64 v[12:13], 11, v[108:109]
	v_lshl_add_u64 v[12:13], v[10:11], 0, v[12:13]
	s_waitcnt vmcnt(6)
	v_lshlrev_b32_e32 v9, 16, v104
	global_store_dwordx4 v[12:13], v[4:7], off sc1 nt
	ds_read_b128 v[4:7], v14 offset:16
	s_waitcnt lgkmcnt(1)
	v_mul_f32_e32 v0, v0, v9
	v_and_b32_e32 v9, 0xffff0000, v104
	v_mul_f32_e32 v1, v1, v9
	v_cvt_pk_bf16_f32 v0, v0, v1
	v_lshlrev_b32_e32 v1, 16, v105
	v_mul_f32_e32 v1, v2, v1
	v_and_b32_e32 v2, 0xffff0000, v105
	v_mul_f32_e32 v2, v3, v2
	v_cvt_pk_bf16_f32 v1, v1, v2
	v_lshlrev_b32_e32 v2, 16, v106
	v_and_b32_e32 v3, 0xffff0000, v106
	s_waitcnt lgkmcnt(0)
	v_mul_f32_e32 v2, v4, v2
	v_mul_f32_e32 v3, v5, v3
	v_cvt_pk_bf16_f32 v2, v2, v3
	v_lshlrev_b32_e32 v3, 16, v107
	v_and_b32_e32 v4, 0xffff0000, v107
	v_mul_f32_e32 v3, v6, v3
	v_mul_f32_e32 v4, v7, v4
	v_mad_u64_u32 v[14:15], s[6:7], v92, s37, v[8:9]
	v_cvt_pk_bf16_f32 v3, v3, v4
	ds_read_b128 v[4:7], v14
	v_ashrrev_i32_e32 v95, 31, v94
	v_lshlrev_b64 v[12:13], 11, v[94:95]
	v_lshl_add_u64 v[12:13], v[10:11], 0, v[12:13]
	s_waitcnt vmcnt(6)
	v_lshlrev_b32_e32 v9, 16, v80
	global_store_dwordx4 v[12:13], v[0:3], off sc1 nt
	ds_read_b128 v[0:3], v14 offset:16
	s_waitcnt lgkmcnt(1)
	v_mul_f32_e32 v4, v4, v9
	v_and_b32_e32 v9, 0xffff0000, v80
	v_mul_f32_e32 v5, v5, v9
	v_cvt_pk_bf16_f32 v4, v4, v5
	v_lshlrev_b32_e32 v5, 16, v81
	v_mul_f32_e32 v5, v6, v5
	v_and_b32_e32 v6, 0xffff0000, v81
	v_mul_f32_e32 v6, v7, v6
	v_cvt_pk_bf16_f32 v5, v5, v6
	v_lshlrev_b32_e32 v6, 16, v82
	s_waitcnt lgkmcnt(0)
	v_mul_f32_e32 v0, v0, v6
	v_and_b32_e32 v6, 0xffff0000, v82
	v_mul_f32_e32 v1, v1, v6
	v_cvt_pk_bf16_f32 v6, v0, v1
	v_lshlrev_b32_e32 v0, 16, v83
	v_and_b32_e32 v1, 0xffff0000, v83
	v_mul_f32_e32 v0, v2, v0
	v_mul_f32_e32 v1, v3, v1
	v_mad_u64_u32 v[14:15], s[6:7], v90, s37, v[8:9]
	v_cvt_pk_bf16_f32 v7, v0, v1
	ds_read_b128 v[0:3], v14
	v_ashrrev_i32_e32 v93, 31, v92
	v_lshlrev_b64 v[12:13], 11, v[92:93]
	v_lshl_add_u64 v[12:13], v[10:11], 0, v[12:13]
	s_waitcnt vmcnt(6)
; __device__ __forceinline__ unsigned cvt_pk(float lo, float hi) { unsigned r; asm volatile("v_cvt_pk_bf16_f32 %0, %1, %2" : "=v"(r) : "v"(lo), "v"(hi)); return r; }
; __device__ __forceinline__ float bflo(unsigned w) { return __uint_as_float(w << 16); }
; __device__ __forceinline__ float bfhi(unsigned w) { return __uint_as_float(w & 0xffff0000u); }
; __device__ __forceinline__ void attn_body(const bf16_t* __restrict__ Qb, const bf16_t* __restrict__ Kh, const bf16_t* __restrict__ Vh, const bf16_t* __restrict__ Zb, ...
;     ...
;     for (int i = 0; i < 8; ++i) { const int idx = tid + 512 * i, row = idx >> 4, c8 = (idx & 15) * 8;
;         const f32x4 a = *(const f32x4*)(Ol + row * 132 + c8), b = *(const f32x4*)(Ol + row * 132 + c8 + 4);
;         const u32x4 z = zr[i];
;         u32x4 w; w.x = cvt_pk(a[0] * bflo(z.x), a[1] * bfhi(z.x)); w.y = cvt_pk(a[2] * bflo(z.y), a[3] * bfhi(z.y));
;         w.z = cvt_pk(b[0] * bflo(z.z), b[1] * bfhi(z.z)); w.w = cvt_pk(b[2] * bflo(z.w), b[3] * bfhi(z.w));
;         *(u32x4*)(Ob + (long)row * 1024 + c8) = w; }
;     __syncthreads();
	v_lshlrev_b32_e32 v9, 16, v76
	global_store_dwordx4 v[12:13], v[4:7], off sc1 nt
	ds_read_b128 v[4:7], v14 offset:16
	s_waitcnt lgkmcnt(1)
	v_mul_f32_e32 v0, v0, v9
	v_and_b32_e32 v9, 0xffff0000, v76
	v_mul_f32_e32 v1, v1, v9
	v_cvt_pk_bf16_f32 v0, v0, v1
	v_lshlrev_b32_e32 v1, 16, v77
	v_mul_f32_e32 v1, v2, v1
	v_and_b32_e32 v2, 0xffff0000, v77
	v_mul_f32_e32 v2, v3, v2
	v_cvt_pk_bf16_f32 v1, v1, v2
	v_lshlrev_b32_e32 v2, 16, v78
	v_and_b32_e32 v3, 0xffff0000, v78
	s_waitcnt lgkmcnt(0)
	v_mul_f32_e32 v2, v4, v2
	v_mul_f32_e32 v3, v5, v3
	v_cvt_pk_bf16_f32 v2, v2, v3
	v_lshlrev_b32_e32 v3, 16, v79
	v_and_b32_e32 v4, 0xffff0000, v79
	v_mul_f32_e32 v3, v6, v3
	v_mul_f32_e32 v4, v7, v4
	v_mad_u64_u32 v[14:15], s[6:7], v88, s37, v[8:9]
	v_cvt_pk_bf16_f32 v3, v3, v4
	ds_read_b128 v[4:7], v14
	v_ashrrev_i32_e32 v91, 31, v90
	v_lshlrev_b64 v[12:13], 11, v[90:91]
	v_lshl_add_u64 v[12:13], v[10:11], 0, v[12:13]
	s_waitcnt vmcnt(6)
	v_lshlrev_b32_e32 v9, 16, v72
	global_store_dwordx4 v[12:13], v[0:3], off sc1 nt
	ds_read_b128 v[0:3], v14 offset:16
	s_waitcnt lgkmcnt(1)
	v_mul_f32_e32 v4, v4, v9
	v_and_b32_e32 v9, 0xffff0000, v72
	v_mul_f32_e32 v5, v5, v9
	v_cvt_pk_bf16_f32 v4, v4, v5
	v_lshlrev_b32_e32 v5, 16, v73
	v_mul_f32_e32 v5, v6, v5
	v_and_b32_e32 v6, 0xffff0000, v73
	v_mul_f32_e32 v6, v7, v6
	v_cvt_pk_bf16_f32 v5, v5, v6
	v_lshlrev_b32_e32 v6, 16, v74
	s_waitcnt lgkmcnt(0)
	v_mul_f32_e32 v0, v0, v6
	v_and_b32_e32 v6, 0xffff0000, v74
	v_mul_f32_e32 v1, v1, v6
	v_cvt_pk_bf16_f32 v6, v0, v1
	v_lshlrev_b32_e32 v0, 16, v75
	v_and_b32_e32 v1, 0xffff0000, v75
	v_mul_f32_e32 v0, v2, v0
	v_mul_f32_e32 v1, v3, v1
	v_mad_u64_u32 v[14:15], s[6:7], v86, s37, v[8:9]
	v_cvt_pk_bf16_f32 v7, v0, v1
	ds_read_b128 v[0:3], v14
	v_ashrrev_i32_e32 v89, 31, v88
	v_lshlrev_b64 v[12:13], 11, v[88:89]
	v_lshl_add_u64 v[12:13], v[10:11], 0, v[12:13]
	s_waitcnt vmcnt(6)
	v_lshlrev_b32_e32 v9, 16, v68
	global_store_dwordx4 v[12:13], v[4:7], off sc1 nt
	ds_read_b128 v[4:7], v14 offset:16
	s_waitcnt lgkmcnt(1)
	v_mul_f32_e32 v0, v0, v9
	v_and_b32_e32 v9, 0xffff0000, v68
	v_mul_f32_e32 v1, v1, v9
	v_cvt_pk_bf16_f32 v0, v0, v1
	v_lshlrev_b32_e32 v1, 16, v69
	v_mul_f32_e32 v1, v2, v1
	v_and_b32_e32 v2, 0xffff0000, v69
	v_mul_f32_e32 v2, v3, v2
	v_cvt_pk_bf16_f32 v1, v1, v2
	v_lshlrev_b32_e32 v2, 16, v70
	v_and_b32_e32 v3, 0xffff0000, v70
	s_waitcnt lgkmcnt(0)
	v_mul_f32_e32 v2, v4, v2
	v_mul_f32_e32 v3, v5, v3
	v_cvt_pk_bf16_f32 v2, v2, v3
	v_lshlrev_b32_e32 v3, 16, v71
	v_and_b32_e32 v4, 0xffff0000, v71
	v_mul_f32_e32 v3, v6, v3
	v_mul_f32_e32 v4, v7, v4
	v_mad_u64_u32 v[8:9], s[6:7], v84, s37, v[8:9]
	v_cvt_pk_bf16_f32 v3, v3, v4
	ds_read_b128 v[4:7], v8
	v_ashrrev_i32_e32 v87, 31, v86
	v_lshlrev_b64 v[12:13], 11, v[86:87]
	v_lshl_add_u64 v[12:13], v[10:11], 0, v[12:13]
	global_store_dwordx4 v[12:13], v[0:3], off sc1 nt
	ds_read_b128 v[0:3], v8 offset:16
	s_waitcnt vmcnt(7)
	v_lshlrev_b32_e32 v8, 16, v64
	s_waitcnt lgkmcnt(1)
	v_mul_f32_e32 v4, v4, v8
	v_and_b32_e32 v8, 0xffff0000, v64
	v_mul_f32_e32 v5, v5, v8
	v_cvt_pk_bf16_f32 v4, v4, v5
	v_lshlrev_b32_e32 v5, 16, v65
	v_mul_f32_e32 v5, v6, v5
	v_and_b32_e32 v6, 0xffff0000, v65
	v_mul_f32_e32 v6, v7, v6
	v_cvt_pk_bf16_f32 v5, v5, v6
	v_lshlrev_b32_e32 v6, 16, v66
	s_waitcnt lgkmcnt(0)
	v_mul_f32_e32 v0, v0, v6
	v_and_b32_e32 v6, 0xffff0000, v66
	v_mul_f32_e32 v1, v1, v6
	v_cvt_pk_bf16_f32 v6, v0, v1
	v_lshlrev_b32_e32 v0, 16, v67
	v_and_b32_e32 v1, 0xffff0000, v67
	v_ashrrev_i32_e32 v85, 31, v84
	v_mul_f32_e32 v0, v2, v0
	v_mul_f32_e32 v1, v3, v1
	v_cvt_pk_bf16_f32 v7, v0, v1
	v_lshlrev_b64 v[0:1], 11, v[84:85]
	s_add_i32 s38, s38, 1
	v_lshl_add_u64 v[0:1], v[10:11], 0, v[0:1]
	s_cmp_lg_u32 s38, 8
	global_store_dwordx4 v[0:1], v[4:7], off sc1 nt
	s_barrier
	s_cbranch_scc0 .LBB0_500
